# prep queue order: attention-prep items (longer) before conv items (shorter), i.e. longest-processing-time first; on top of previous best
# baseline (speedup 1.0000x reference)
; __global__ void __launch_bounds__(512, 2) mk_fwd(Args args) {
;     ...
;             while (it < N_C + N_A + N_D + N_B) {
;                 int nx = 0; if (F.tid == 0) nx = 256 + (int)__hip_atomic_fetch_add(qctr, 1u, __ATOMIC_RELAXED, __HIP_MEMORY_SCOPE_AGENT);
;                 int r = it; PH_PTRS;
;                 if (r < N_C) { if (sel & 1) cprep_item(Fp, args, lp, r, P, wsp); }
;                 else if ((r -= N_C) < N_A) { if (sel & 4) { if (r < 256) gmlp_item(Fp, args, lp, r >> 2, r & 3, P, ACT); else gmlp_sample_item(Fp, args, lp, P, ACT); } }
;                 else if ((r -= N_A) < N_D) { if (sel & 2) dconv_item(Fp, args, lp, r, P, ACT + (size_t)3 * MPAD * BW); }
;                 else { r -= N_D; if (sel & 8) bprep_item(Fp, args, lp, r, P, QB, KB, VT, QS); }
.LBB0_213:
	s_cmpk_lt_i32 s26, 0x202
	s_cbranch_scc1 .Lprep_order_done
	s_movk_i32 s1, 0xfeff
	s_cmpk_lt_i32 s26, 0x303
	s_cselect_b32 s0, 0x108, s1
	s_add_i32 s26, s26, s0
